# XCD census check after the first barrier: the eight counter loads issued together with one wait instead of a load-wait-compare ladder
# baseline (speedup 1.0000x reference)
; #define LAS __attribute__((address_space(3)))
; __global__ void __launch_bounds__(512, 2) mk_fwd(Args a) {
;     ...
;       if (threadIdx.x == 0) { const unsigned my_rank = *(LAS unsigned*)(lds + RING_BYTES + 64); bool ok = (G % 8 == 0) && (my_xcc < 8u);
;           for (int j = 0; j < 8; ++j) ok = ok && (__hip_atomic_load(bar_ctr + 512 + 64 * j, __ATOMIC_RELAXED, __HIP_MEMORY_SCOPE_AGENT) == (unsigned)(G / 8));
;           *vslot = ok ? (int)(my_rank * 8u + my_xcc) : bx; }
.Lmy_gb1_done:
.LBB0_82:
	s_or_b64 exec, exec, s[4:5]
	s_barrier
	s_mov_b64 s[4:5], exec
	v_readlane_b32 s0, v255, 0
	v_readlane_b32 s1, v255, 1
	s_and_b64 s[0:1], s[4:5], s[0:1]
	s_mov_b64 exec, s[0:1]
	s_cbranch_execz .LBB0_93
	s_add_i32 s1, 0, 0x20040
	s_and_b32 s0, s3, 15
	v_mov_b32_e32 v0, s1
	s_and_b32 s1, s24, 7
	ds_read_b32 v0, v0
	s_cmp_eq_u32 s1, 0
	s_cselect_b64 s[6:7], -1, 0
	s_cmp_lt_u32 s0, 8
	s_cselect_b64 s[8:9], -1, 0
	s_and_b64 s[6:7], s[6:7], s[8:9]
	s_andn2_b64 vcc, exec, s[6:7]
	s_mov_b64 s[6:7], 0
	s_cbranch_vccnz .LBB0_92
	v_mov_b32_e32 v1, 0
	global_load_dword v2, v1, s[22:23] offset:2048 sc1
	global_load_dword v3, v1, s[22:23] offset:2304 sc1
	global_load_dword v4, v1, s[22:23] offset:2560 sc1
	global_load_dword v5, v1, s[22:23] offset:2816 sc1
	global_load_dword v6, v1, s[22:23] offset:3072 sc1
	global_load_dword v7, v1, s[22:23] offset:3328 sc1
	global_load_dword v8, v1, s[22:23] offset:3584 sc1
	global_load_dword v9, v1, s[22:23] offset:3840 sc1
	s_ashr_i32 s1, s24, 31
	s_lshr_b32 s1, s1, 29
	s_add_i32 s1, s24, s1
	s_ashr_i32 s1, s1, 3
	s_waitcnt vmcnt(0)
	v_xor_b32_e32 v2, s1, v2
	v_xor_b32_e32 v3, s1, v3
	v_xor_b32_e32 v4, s1, v4
	v_xor_b32_e32 v5, s1, v5
	v_xor_b32_e32 v6, s1, v6
	v_xor_b32_e32 v7, s1, v7
	v_xor_b32_e32 v8, s1, v8
	v_xor_b32_e32 v9, s1, v9
	v_or3_b32 v2, v2, v3, v4
	v_or3_b32 v5, v5, v6, v7
	v_or3_b32 v2, v2, v5, v8
	v_or_b32_e32 v2, v2, v9
	v_cmp_eq_u32_e64 s[6:7], 0, v2
